# E18: down-skinny non-last chunks get own compute block with A0 waits relaxed by 8 (next-chunk weight loads stay in flight); on E10
# baseline (speedup 1.0000x reference)
.Lsk_more0:
	ds_read_b128 v[182:185], v180
	ds_read_b128 v[186:189], v180 offset:32
	v_lshl_add_u64 v[142:143], v[142:143], 0, s[26:27]
	v_lshl_add_u64 v[144:145], v[144:145], 0, s[26:27]
	v_lshl_add_u64 v[146:147], v[146:147], 0, s[26:27]
	s_waitcnt vmcnt(17) lgkmcnt(1)
	v_mfma_f32_32x32x16_bf16 v[4:19], v[182:185], v[124:127], v[4:19]
	v_lshl_add_u64 v[148:149], v[148:149], 0, s[26:27]
	v_lshl_add_u64 v[150:151], v[150:151], 0, s[26:27]
	v_lshl_add_u64 v[152:153], v[152:153], 0, s[26:27]
	v_lshl_add_u64 v[154:155], v[154:155], 0, s[26:27]
	v_lshl_add_u64 v[156:157], v[156:157], 0, s[26:27]
	v_lshl_add_u64 v[158:159], v[158:159], 0, s[28:29]
	v_lshl_add_u64 v[160:161], v[160:161], 0, s[28:29]
	s_waitcnt vmcnt(11)
	v_mfma_f32_32x32x16_bf16 v[20:35], v[182:185], v[128:131], v[20:35]
	s_cmp_lg_u32 s31, s6
	s_waitcnt lgkmcnt(0)
	v_mfma_f32_32x32x16_bf16 v[4:19], v[186:189], v[116:119], v[4:19]
	v_mfma_f32_32x32x16_bf16 v[20:35], v[186:189], v[120:123], v[20:35]
	ds_read_b128 v[116:119], v180 offset:64
	ds_read_b128 v[120:123], v180 offset:96
	s_waitcnt lgkmcnt(1)
	v_mfma_f32_32x32x16_bf16 v[4:19], v[116:119], v[100:103], v[4:19]
	v_mfma_f32_32x32x16_bf16 v[20:35], v[116:119], v[112:115], v[20:35]
	s_waitcnt lgkmcnt(0)
	v_mfma_f32_32x32x16_bf16 v[4:19], v[120:123], v[104:107], v[4:19]
	ds_read_b128 v[100:103], v180 offset:128
	ds_read_b128 v[104:107], v180 offset:160
	v_mfma_f32_32x32x16_bf16 v[20:35], v[120:123], v[108:111], v[20:35]
	s_waitcnt lgkmcnt(1)
	v_mfma_f32_32x32x16_bf16 v[4:19], v[100:103], v[88:91], v[4:19]
	v_mfma_f32_32x32x16_bf16 v[20:35], v[100:103], v[92:95], v[20:35]
	v_add_co_u32_e32 v100, vcc, s41, v162
	s_nop 1
	v_addc_co_u32_e32 v101, vcc, 0, v163, vcc
	v_add_co_u32_e32 v102, vcc, s41, v164
	s_waitcnt lgkmcnt(0)
	v_mfma_f32_32x32x16_bf16 v[4:19], v[104:107], v[96:99], v[4:19]
	v_addc_co_u32_e32 v103, vcc, 0, v165, vcc
	v_mfma_f32_32x32x16_bf16 v[20:35], v[104:107], v[84:87], v[20:35]
	ds_read_b128 v[84:87], v180 offset:192
	ds_read_b128 v[88:91], v180 offset:224
	v_add_co_u32_e32 v104, vcc, s40, v162
	ds_read_b128 v[92:95], v180 offset:288
	s_nop 0
	v_addc_co_u32_e32 v105, vcc, 0, v163, vcc
	v_add_co_u32_e32 v106, vcc, s40, v164
	s_waitcnt lgkmcnt(2)
	v_mfma_f32_32x32x16_bf16 v[4:19], v[84:87], v[80:83], v[4:19]
	global_load_dwordx4 v[80:83], v[100:101], off offset:-4096
	v_addc_co_u32_e32 v107, vcc, 0, v165, vcc
	s_waitcnt vmcnt(10)
	v_mfma_f32_32x32x16_bf16 v[20:35], v[84:87], v[76:79], v[20:35]
	global_load_dwordx4 v[76:79], v[102:103], off offset:-4096
	ds_read_b128 v[84:87], v180 offset:256
	s_waitcnt lgkmcnt(2)
	v_mfma_f32_32x32x16_bf16 v[4:19], v[88:91], v[72:75], v[4:19]
	global_load_dwordx4 v[72:75], v[104:105], off offset:1024
	s_waitcnt vmcnt(11)
	v_mfma_f32_32x32x16_bf16 v[20:35], v[88:91], v[68:71], v[20:35]
	global_load_dwordx4 v[68:71], v[106:107], off offset:1024
	global_load_dwordx4 v[88:91], v[100:101], off
	s_waitcnt vmcnt(4) lgkmcnt(0)
	v_mfma_f32_32x32x16_bf16 v[4:19], v[84:87], v[80:83], v[4:19]
	global_load_dwordx4 v[80:83], v[104:105], off offset:2048
	global_load_dwordx4 v[96:99], v[100:101], off offset:3072
	s_waitcnt vmcnt(5)
	v_mfma_f32_32x32x16_bf16 v[20:35], v[84:87], v[76:79], v[20:35]
	global_load_dwordx4 v[76:79], v[106:107], off offset:2048
	s_waitcnt vmcnt(5)
	v_mfma_f32_32x32x16_bf16 v[4:19], v[92:95], v[72:75], v[4:19]
	global_load_dwordx4 v[72:75], v[104:105], off offset:3072
	s_waitcnt vmcnt(5)
	v_mfma_f32_32x32x16_bf16 v[20:35], v[92:95], v[68:71], v[20:35]
	ds_read_b128 v[68:71], v180 offset:320
	ds_read_b128 v[84:87], v180 offset:352
	s_waitcnt vmcnt(3) lgkmcnt(1)
	v_mfma_f32_32x32x16_bf16 v[4:19], v[68:71], v[80:83], v[4:19]
	global_load_dwordx4 v[80:83], v[106:107], off offset:3072
	s_waitcnt vmcnt(2)
	v_mfma_f32_32x32x16_bf16 v[20:35], v[68:71], v[76:79], v[20:35]
	global_load_dwordx4 v[68:71], v[102:103], off
	global_load_dwordx4 v[76:79], v[100:101], off offset:1024
	s_waitcnt vmcnt(3) lgkmcnt(0)
	v_mfma_f32_32x32x16_bf16 v[4:19], v[84:87], v[72:75], v[4:19]
	ds_read_b128 v[72:75], v180 offset:384
	s_waitcnt vmcnt(2)
	v_mfma_f32_32x32x16_bf16 v[20:35], v[84:87], v[80:83], v[20:35]
	global_load_dwordx4 v[84:87], v[102:103], off offset:1024
	ds_read_b128 v[80:83], v180 offset:416
	s_waitcnt vmcnt(2) lgkmcnt(1)
	v_mfma_f32_32x32x16_bf16 v[20:35], v[72:75], v[68:71], v[20:35]
	global_load_dwordx4 v[68:71], v[100:101], off offset:2048
	v_mfma_f32_32x32x16_bf16 v[4:19], v[72:75], v[88:91], v[4:19]
	global_load_dwordx4 v[72:75], v[102:103], off offset:2048
	s_waitcnt vmcnt(3) lgkmcnt(0)
	v_mfma_f32_32x32x16_bf16 v[4:19], v[80:83], v[76:79], v[4:19]
	s_waitcnt vmcnt(2)
	v_mfma_f32_32x32x16_bf16 v[20:35], v[80:83], v[84:87], v[20:35]
	ds_read_b128 v[76:79], v180 offset:448
	ds_read_b128 v[80:83], v180 offset:480
	s_waitcnt vmcnt(1) lgkmcnt(1)
	v_mfma_f32_32x32x16_bf16 v[4:19], v[76:79], v[68:71], v[4:19]
	global_load_dwordx4 v[68:71], v[102:103], off offset:3072
	s_waitcnt vmcnt(1)
	v_mfma_f32_32x32x16_bf16 v[20:35], v[76:79], v[72:75], v[20:35]
	s_waitcnt lgkmcnt(0)
	v_mfma_f32_32x32x16_bf16 v[4:19], v[80:83], v[96:99], v[4:19]
	s_waitcnt vmcnt(0)
	v_mfma_f32_32x32x16_bf16 v[20:35], v[80:83], v[68:71], v[20:35]
	s_cbranch_scc0 .LBB0_892
	s_branch .LBB0_890

.Lsk_more1:
	ds_read_b128 v[178:181], v176
	ds_read_b128 v[182:185], v176 offset:32
	v_lshl_add_u64 v[138:139], v[138:139], 0, s[24:25]
	v_lshl_add_u64 v[140:141], v[140:141], 0, s[24:25]
	v_lshl_add_u64 v[142:143], v[142:143], 0, s[24:25]
	s_waitcnt vmcnt(17) lgkmcnt(1)
	v_mfma_f32_32x32x16_bf16 v[2:17], v[178:181], v[122:125], v[2:17]
	v_lshl_add_u64 v[144:145], v[144:145], 0, s[24:25]
	v_lshl_add_u64 v[146:147], v[146:147], 0, s[24:25]
	v_lshl_add_u64 v[148:149], v[148:149], 0, s[24:25]
	v_lshl_add_u64 v[150:151], v[150:151], 0, s[24:25]
	v_lshl_add_u64 v[152:153], v[152:153], 0, s[24:25]
	v_lshl_add_u64 v[154:155], v[154:155], 0, s[26:27]
	v_lshl_add_u64 v[156:157], v[156:157], 0, s[26:27]
	s_waitcnt vmcnt(11)
	v_mfma_f32_32x32x16_bf16 v[18:33], v[178:181], v[126:129], v[18:33]
	s_cmp_lg_u32 s29, s6
	s_waitcnt lgkmcnt(0)
	v_mfma_f32_32x32x16_bf16 v[2:17], v[182:185], v[114:117], v[2:17]
	v_mfma_f32_32x32x16_bf16 v[18:33], v[182:185], v[118:121], v[18:33]
	ds_read_b128 v[114:117], v176 offset:64
	ds_read_b128 v[118:121], v176 offset:96
	s_waitcnt lgkmcnt(1)
	v_mfma_f32_32x32x16_bf16 v[2:17], v[114:117], v[98:101], v[2:17]
	v_mfma_f32_32x32x16_bf16 v[18:33], v[114:117], v[110:113], v[18:33]
	s_waitcnt lgkmcnt(0)
	v_mfma_f32_32x32x16_bf16 v[2:17], v[118:121], v[102:105], v[2:17]
	ds_read_b128 v[98:101], v176 offset:128
	ds_read_b128 v[102:105], v176 offset:160
	v_mfma_f32_32x32x16_bf16 v[18:33], v[118:121], v[106:109], v[18:33]
	s_waitcnt lgkmcnt(1)
	v_mfma_f32_32x32x16_bf16 v[2:17], v[98:101], v[86:89], v[2:17]
	v_mfma_f32_32x32x16_bf16 v[18:33], v[98:101], v[90:93], v[18:33]
	v_add_co_u32_e32 v98, vcc, s39, v158
	s_nop 1
	v_addc_co_u32_e32 v99, vcc, 0, v159, vcc
	v_add_co_u32_e32 v100, vcc, s39, v160
	s_waitcnt lgkmcnt(0)
	v_mfma_f32_32x32x16_bf16 v[2:17], v[102:105], v[94:97], v[2:17]
	v_addc_co_u32_e32 v101, vcc, 0, v161, vcc
	v_mfma_f32_32x32x16_bf16 v[18:33], v[102:105], v[82:85], v[18:33]
	ds_read_b128 v[82:85], v176 offset:192
	ds_read_b128 v[86:89], v176 offset:224
	v_add_co_u32_e32 v102, vcc, s38, v158
	ds_read_b128 v[90:93], v176 offset:288
	s_nop 0
	v_addc_co_u32_e32 v103, vcc, 0, v159, vcc
	v_add_co_u32_e32 v104, vcc, s38, v160
	s_waitcnt lgkmcnt(2)
	v_mfma_f32_32x32x16_bf16 v[2:17], v[82:85], v[78:81], v[2:17]
	global_load_dwordx4 v[78:81], v[98:99], off offset:-4096
	v_addc_co_u32_e32 v105, vcc, 0, v161, vcc
	s_waitcnt vmcnt(10)
	v_mfma_f32_32x32x16_bf16 v[18:33], v[82:85], v[74:77], v[18:33]
	global_load_dwordx4 v[74:77], v[100:101], off offset:-4096
	ds_read_b128 v[82:85], v176 offset:256
	s_waitcnt lgkmcnt(2)
	v_mfma_f32_32x32x16_bf16 v[2:17], v[86:89], v[70:73], v[2:17]
	global_load_dwordx4 v[70:73], v[102:103], off offset:1024
	s_waitcnt vmcnt(11)
	v_mfma_f32_32x32x16_bf16 v[18:33], v[86:89], v[66:69], v[18:33]
	global_load_dwordx4 v[66:69], v[104:105], off offset:1024
	global_load_dwordx4 v[86:89], v[98:99], off
	s_waitcnt vmcnt(4) lgkmcnt(0)
	v_mfma_f32_32x32x16_bf16 v[2:17], v[82:85], v[78:81], v[2:17]
	global_load_dwordx4 v[78:81], v[102:103], off offset:2048
	global_load_dwordx4 v[94:97], v[98:99], off offset:3072
	s_waitcnt vmcnt(5)
	v_mfma_f32_32x32x16_bf16 v[18:33], v[82:85], v[74:77], v[18:33]
	global_load_dwordx4 v[74:77], v[104:105], off offset:2048
	s_waitcnt vmcnt(5)
	v_mfma_f32_32x32x16_bf16 v[2:17], v[90:93], v[70:73], v[2:17]
	global_load_dwordx4 v[70:73], v[102:103], off offset:3072
	s_waitcnt vmcnt(5)
	v_mfma_f32_32x32x16_bf16 v[18:33], v[90:93], v[66:69], v[18:33]
	ds_read_b128 v[66:69], v176 offset:320
	ds_read_b128 v[82:85], v176 offset:352
	s_waitcnt vmcnt(3) lgkmcnt(1)
	v_mfma_f32_32x32x16_bf16 v[2:17], v[66:69], v[78:81], v[2:17]
	global_load_dwordx4 v[78:81], v[104:105], off offset:3072
	s_waitcnt vmcnt(2)
	v_mfma_f32_32x32x16_bf16 v[18:33], v[66:69], v[74:77], v[18:33]
	global_load_dwordx4 v[66:69], v[100:101], off
	global_load_dwordx4 v[74:77], v[98:99], off offset:1024
	s_waitcnt vmcnt(3) lgkmcnt(0)
	v_mfma_f32_32x32x16_bf16 v[2:17], v[82:85], v[70:73], v[2:17]
	ds_read_b128 v[70:73], v176 offset:384
	s_waitcnt vmcnt(2)
	v_mfma_f32_32x32x16_bf16 v[18:33], v[82:85], v[78:81], v[18:33]
	global_load_dwordx4 v[82:85], v[100:101], off offset:1024
	ds_read_b128 v[78:81], v176 offset:416
	s_waitcnt vmcnt(2) lgkmcnt(1)
	v_mfma_f32_32x32x16_bf16 v[18:33], v[70:73], v[66:69], v[18:33]
	global_load_dwordx4 v[66:69], v[98:99], off offset:2048
	v_mfma_f32_32x32x16_bf16 v[2:17], v[70:73], v[86:89], v[2:17]
	global_load_dwordx4 v[70:73], v[100:101], off offset:2048
	s_waitcnt vmcnt(3) lgkmcnt(0)
	v_mfma_f32_32x32x16_bf16 v[2:17], v[78:81], v[74:77], v[2:17]
	s_waitcnt vmcnt(2)
	v_mfma_f32_32x32x16_bf16 v[18:33], v[78:81], v[82:85], v[18:33]
	ds_read_b128 v[74:77], v176 offset:448
	ds_read_b128 v[78:81], v176 offset:480
	s_waitcnt vmcnt(1) lgkmcnt(1)
	v_mfma_f32_32x32x16_bf16 v[2:17], v[74:77], v[66:69], v[2:17]
	global_load_dwordx4 v[66:69], v[100:101], off offset:3072
	s_waitcnt vmcnt(1)
	v_mfma_f32_32x32x16_bf16 v[18:33], v[74:77], v[70:73], v[18:33]
	s_waitcnt lgkmcnt(0)
	v_mfma_f32_32x32x16_bf16 v[2:17], v[78:81], v[94:97], v[2:17]
	s_waitcnt vmcnt(0)
	v_mfma_f32_32x32x16_bf16 v[18:33], v[78:81], v[66:69], v[18:33]
	s_cbranch_scc0 .LBB0_1825
	s_branch .LBB0_1823
